# per-XCD phase-5 queue with fallback to the single global queue when the XCC census does not report 8 XCDs
# speedup vs baseline: 1.0147x; 1.0018x over previous
; DI void phase5(const Params& p, int l, unsigned char* smem) {
;   __shared__ int s_task;
;   int* ctr = (int*)(p.ws + W_CTR) + l;
.LBB0_770:
	v_writelane_b32 v254, s42, 56
	s_nop 1
	v_writelane_b32 v254, s43, 57
	s_or_b64 exec, exec, s[2:3]
	v_readlane_b32 s2, v254, 49
	s_barrier
	s_ashr_i32 s3, s2, 31
	s_lshl_b64 s[4:5], s[2:3], 2
	s_add_u32 s3, s76, s4
	s_addc_u32 s4, s77, s5
	s_add_u32 s34, s3, 0x2ac8000
	s_addc_u32 s35, s4, 0
	v_mov_b32_e32 v0, 0x12100
	ds_read_b32 v0, v0 offset:4
	s_getreg_b32 s5, hwreg(HW_REG_XCC_ID, 0, 4)
	s_and_b32 s5, s5, 7
	v_writelane_b32 v255, s5, 56
	s_lshl_b32 s5, s5, 4
	s_add_u32 s5, s5, 64
	s_waitcnt lgkmcnt(0)
	v_readfirstlane_b32 s4, v0
	s_nop 3
	s_cmp_eq_u32 s4, 8
	s_cselect_b32 s5, s5, 0
	s_movk_i32 s4, 0xb7f
	s_cselect_b32 s4, 0x16f, s4
	v_writelane_b32 v255, s4, 54
	s_cselect_b32 s4, 1, 0
	v_writelane_b32 v255, s4, 55
	s_add_u32 s34, s34, s5
	s_addc_u32 s35, s35, 0
	s_lshl_b32 s3, s2, 6
	v_writelane_b32 v254, s3, 58
	s_lshl_b32 s2, s2, 4
	v_writelane_b32 v254, s2, 59
	s_nop 0
	v_readlane_b32 s2, v254, 37
	v_readlane_b32 s3, v254, 38
	s_add_u32 s4, s2, 0x1898d000
	v_writelane_b32 v254, s4, 60
	s_addc_u32 s4, s3, 0
	s_add_u32 s80, s76, 0x7b6b700
	s_addc_u32 s81, s77, 0
	v_writelane_b32 v254, s4, 61
	s_add_u32 s2, s2, 0x4080000
	v_writelane_b32 v254, s2, 63
	s_addc_u32 s2, s3, 0
	v_writelane_b32 v255, s2, 0
	s_add_u32 s2, s76, 0x23ebcf00
	v_writelane_b32 v255, s2, 1
	s_addc_u32 s2, s77, 0
	v_writelane_b32 v255, s2, 2
	v_writelane_b32 v255, s80, 3
	s_nop 1
	v_writelane_b32 v255, s81, 4
	v_writelane_b32 v255, s40, 5
	s_nop 1
	v_writelane_b32 v255, s41, 6
	v_writelane_b32 v255, s34, 7
	s_nop 1
	v_writelane_b32 v255, s35, 8
	s_branch .LBB0_774

; DI void phase5(const Params& p, int l, unsigned char* smem) {
;     ...
;     int q = s_task;
;     if (q >= PH5_TASKS) break;
;     int task = q < 1024 ? ((q & 1) ? 512 + (q >> 1) : (q >> 1)) : q;
;     phase5_task(p, l, task, smem);
.LBB0_778:
	s_or_b64 exec, exec, s[2:3]
	s_waitcnt lgkmcnt(0)
	s_barrier
	ds_read_b32 v0, v184
	v_readlane_b32 s2, v255, 54
	s_nop 1
	s_waitcnt lgkmcnt(0)
	v_cmp_lt_i32_e32 vcc, s2, v0
	v_readfirstlane_b32 s4, v0
	s_mov_b64 s[2:3], -1
	s_cbranch_vccnz .LBB0_773
	v_readlane_b32 s3, v255, 55
	v_readlane_b32 s2, v255, 56
	s_nop 3
	s_cmp_eq_u32 s3, 0
	s_cbranch_scc0 .Lp5q_xcd
	s_lshl_b32 s3, s4, 9
	s_ashr_i32 s2, s4, 1
	s_and_b32 s3, s3, 0x200
	s_add_i32 s3, s3, s2
	s_cmpk_lt_i32 s4, 0x400
	s_cselect_b32 s50, s3, s4
	s_branch .Lp5_task
.Lp5q_xcd:
	s_cmpk_lt_u32 s4, 0x80
	s_cbranch_scc0 .Lp5q_hi
	s_lshr_b32 s3, s4, 1
	s_bitcmp1_b32 s4, 0
	s_cbranch_scc1 .Lp5q_odd
	s_and_b32 s50, s3, 1
	s_lshl_b32 s2, s2, 1
	s_add_i32 s50, s50, s2
	s_lshl_b32 s50, s50, 5
	s_lshr_b32 s3, s3, 1
	s_add_i32 s50, s50, s3
	s_branch .Lp5_task
